# selected-block attention: bias table in LDS plus the 64-token-block token mapping with the block's two neighbour blocks (cur-1, cur) staged in LDS
# speedup vs baseline: 1.0731x; 1.0092x over previous
.LBB0_841:
	s_andn2_b64 vcc, exec, s[0:1]
	v_readlane_b32 s3, v254, 47
	s_cbranch_vccnz .LBB0_934
	s_mov_b64 s[22:23], exec
	s_and_b32 s2, s3, 1
	s_lshr_b32 s0, s3, 1
	s_and_b32 s0, s0, 3
	s_lshl_b32 s26, s0, 6
	s_lshr_b32 s0, s3, 3
	s_add_i32 s26, s26, s0
	s_mov_b32 s61, s26
	s_lshl_b32 s26, s26, 6
	v_readfirstlane_b32 s1, v220
	s_lshl_b32 s0, s1, 3
	s_add_i32 s26, s26, s0
	s_mov_b32 s60, 0
	s_lshl_b32 s0, s2, 6
	s_add_u32 s12, s12, s0
	s_addc_u32 s13, s13, 0
	s_lshl_b32 s0, s2, 21
	s_add_u32 s18, s18, s0
	s_addc_u32 s19, s19, 0
	s_add_u32 s16, s16, s0
	s_addc_u32 s17, s17, 0
	v_lshl_or_b32 v202, s2, 3, v200
	s_lshl_b32 s63, s2, 3
	v_and_b32_e32 v140, 63, v208
	v_lshlrev_b32_e32 v140, 4, v140
	v_add_u32_e32 v141, 0x1000, v140
	s_mov_b32 s48, 0x3e38aa3b
	s_mov_b32 s49, 0x3e38aa3b
	s_mov_b32 s57, 0x20400
	v_mov_b32_e32 v179, 0xf149f2ca
	v_lshl_add_u32 v66, v202, 2, s57
	ds_read_b32 v178, v66 offset:1984
	s_barrier
	s_and_b32 s0, s1, 3
	s_lshl_b32 s0, s0, 11
	s_cmp_lt_u32 s1, 4
	s_cselect_b32 s40, s18, s16
	s_cselect_b32 s41, s19, s17
	s_cselect_b32 s2, 0, 0x2000
	s_add_u32 s40, s40, s0
	s_addc_u32 s41, s41, 0
	s_add_i32 s2, s2, s0
	s_mov_b32 m0, s2
	s_nop 0
	global_load_lds_dwordx4 v140, s[40:41]
	s_add_u32 s40, s40, 0x400
	s_addc_u32 s41, s41, 0
	s_add_i32 m0, s2, 0x400
	s_nop 0
	global_load_lds_dwordx4 v140, s[40:41]
	v_mov_b32_e32 v66, v208
	s_mov_b32 s0, 26
.Lsel_lut:
	v_lshrrev_b32_e32 v67, 3, v66
	v_add_u32_e32 v67, 0xffffffc0, v67
	v_and_b32_e32 v144, 7, v66
	v_max_i32_e32 v145, 0, v67
	v_cvt_f32_u32_e32 v143, v145
	v_mul_f32_e32 v143, 0x3d800000, v143
	v_log_f32_e32 v143, v143
	s_nop 0
	v_mul_f32_e32 v143, 0x40124925, v143
	v_cvt_i32_f32_e32 v143, v143
	v_med3_i32 v143, v143, 0, 15
	v_add_u32_e32 v143, 16, v143
	v_cmp_gt_u32_e32 vcc, 16, v145
	s_nop 1
	v_cndmask_b32_e32 v143, v143, v145, vcc
	v_lshl_add_u32 v143, v143, 4, v144
	v_add_u32_e32 v143, s63, v143
	v_lshl_add_u32 v143, v143, 2, s57
	ds_read_b32 v143, v143
	v_cmp_le_i32_e32 vcc, 0, v67
	s_waitcnt lgkmcnt(0)
	v_mul_f32_e32 v143, 0x3fb8aa3b, v143
	v_cndmask_b32_e32 v143, v179, v143, vcc
	v_lshlrev_b32_e32 v177, 2, v66
	v_add_u32_e32 v177, 0xc000, v177
	ds_write_b32 v177, v143
	v_add_u32_e32 v66, 0x200, v66
	s_add_i32 s0, s0, -1
	s_cmp_lg_u32 s0, 0
	s_cbranch_scc1 .Lsel_lut
	s_waitcnt lgkmcnt(0)
	v_readfirstlane_b32 s1, v220
	s_waitcnt lgkmcnt(0)
	s_barrier
	s_and_b32 s0, s1, 3
	s_lshl_b32 s0, s0, 12
	s_cmp_lt_u32 s1, 4
	s_cselect_b32 s40, s18, s16
	s_cselect_b32 s41, s19, s17
	s_cselect_b32 s2, 1, 2
	s_lshl_b32 s2, s2, 14
	s_add_i32 s2, s2, s0
	s_add_i32 s62, s61, -1
	s_lshl_b32 s62, s62, 13
	s_add_i32 s0, s0, s62
	s_ashr_i32 s62, s0, 31
	s_add_u32 s40, s40, s0
	s_addc_u32 s41, s41, s62
	s_add_i32 m0, s2, 0
	s_nop 0
	global_load_lds_dwordx4 v140, s[40:41]
	s_add_i32 m0, s2, 1024
	s_add_u32 s40, s40, 0x400
	s_addc_u32 s41, s41, 0
	global_load_lds_dwordx4 v140, s[40:41]
	s_add_i32 m0, s2, 2048
	s_add_u32 s40, s40, 0x400
	s_addc_u32 s41, s41, 0
	global_load_lds_dwordx4 v140, s[40:41]
	s_add_i32 m0, s2, 3072
	s_add_u32 s40, s40, 0x400
	s_addc_u32 s41, s41, 0
	global_load_lds_dwordx4 v140, s[40:41]
	s_waitcnt vmcnt(0)
	s_barrier
	s_lshl_b32 s0, s26, 7
	s_add_u32 s38, s12, s0
	s_addc_u32 s39, s13, 0
	v_lshrrev_b32_e32 v144, 3, v199
	global_load_dword v176, v144, s[38:39]
	s_lshl_b32 s0, s26, 11
	s_add_u32 s54, s14, s0
	s_addc_u32 s55, s15, 0
	v_lshlrev_b32_e32 v67, 7, v202
	v_lshl_add_u32 v67, v198, 1, v67
	global_load_dwordx4 v[16:19], v67, s[54:55]
	global_load_dwordx4 v[20:23], v67, s[54:55] offset:64
	s_mov_b64 s[34:35], s[18:19]
	s_mov_b64 s[36:37], s[16:17]
	ds_read_b128 v[32:35], v140 offset:0
	ds_read_b128 v[36:39], v140 offset:1024
	ds_read_b128 v[40:43], v140 offset:2048
	ds_read_b128 v[44:47], v140 offset:3072
	ds_read_b128 v[48:51], v140 offset:4096
	ds_read_b128 v[52:55], v140 offset:5120
	ds_read_b128 v[56:59], v140 offset:6144
	ds_read_b128 v[60:63], v140 offset:7168
	ds_read_b128 v[100:103], v140 offset:8192
	ds_read_b128 v[104:107], v140 offset:9216
	ds_read_b128 v[108:111], v140 offset:10240
	ds_read_b128 v[112:115], v140 offset:11264
	ds_read_b128 v[116:119], v140 offset:12288
	ds_read_b128 v[120:123], v140 offset:13312
	ds_read_b128 v[124:127], v140 offset:14336
	ds_read_b128 v[128:131], v140 offset:15360
	s_lshr_b32 s0, s26, 6
	s_add_i32 s0, s0, 1
	s_min_i32 s28, s0, 16
	s_mov_b32 s29, 0
	s_mov_b32 s30, 0
	s_mov_b32 s51, 0
	v_mov_b32_e32 v196, 0xf149f2ca
	v_mov_b32_e32 v197, 0
	v_mov_b32_e32 v0, 0
	v_mov_b32_e32 v1, 0
	v_mov_b32_e32 v2, 0
	v_mov_b32_e32 v3, 0
	v_mov_b32_e32 v4, 0
	v_mov_b32_e32 v5, 0
	v_mov_b32_e32 v6, 0
	v_mov_b32_e32 v7, 0
	v_mov_b32_e32 v8, 0
	v_mov_b32_e32 v9, 0
	v_mov_b32_e32 v10, 0
	v_mov_b32_e32 v11, 0
	v_mov_b32_e32 v12, 0
	v_mov_b32_e32 v13, 0
	v_mov_b32_e32 v14, 0
	v_mov_b32_e32 v15, 0
	s_waitcnt lgkmcnt(0)
	v_mul_f32_e32 v178, 0x3fb8aa3b, v178
	s_waitcnt vmcnt(2)

.Lsel_slow:
	s_add_i32 s1, s0, 13
	s_lshl_b32 s1, s1, 5
	s_add_i32 s1, s1, 0xc000
	v_lshlrev_b32_e32 v66, 5, v182
	v_sub_u32_e32 v66, s1, v66
	v_lshl_add_u32 v66, v200, 2, v66
	ds_read_b32 v222, v66 offset:1632
	ds_read_b32 v223, v66 offset:1600
	ds_read_b32 v224, v66 offset:1568
	ds_read_b32 v225, v66 offset:1536
	ds_read_b32 v226, v66 offset:1120
	ds_read_b32 v227, v66 offset:1088
	ds_read_b32 v228, v66 offset:1056
	ds_read_b32 v229, v66 offset:1024
	ds_read_b32 v230, v66 offset:608
	ds_read_b32 v231, v66 offset:576
	ds_read_b32 v232, v66 offset:544
	ds_read_b32 v233, v66 offset:512
	ds_read_b32 v234, v66 offset:96
	ds_read_b32 v235, v66 offset:64
	ds_read_b32 v236, v66 offset:32
	ds_read_b32 v237, v66 offset:0
	s_waitcnt lgkmcnt(0)
	v_pk_fma_f32 v[184:185], v[184:185], s[48:49], v[222:223] op_sel_hi:[1,0,1]
	v_pk_fma_f32 v[186:187], v[186:187], s[48:49], v[224:225] op_sel_hi:[1,0,1]
	v_pk_fma_f32 v[188:189], v[188:189], s[48:49], v[226:227] op_sel_hi:[1,0,1]
	v_pk_fma_f32 v[190:191], v[190:191], s[48:49], v[228:229] op_sel_hi:[1,0,1]
	v_pk_fma_f32 v[192:193], v[192:193], s[48:49], v[230:231] op_sel_hi:[1,0,1]
	v_pk_fma_f32 v[194:195], v[194:195], s[48:49], v[232:233] op_sel_hi:[1,0,1]
	v_pk_fma_f32 v[172:173], v[172:173], s[48:49], v[234:235] op_sel_hi:[1,0,1]
	v_pk_fma_f32 v[174:175], v[174:175], s[48:49], v[236:237] op_sel_hi:[1,0,1]
	s_cmp_eq_u32 s51, 0
	s_cbranch_scc1 .Lsel_maxA
	s_branch .Lsel_maxB
